# unreachable compiler EpiOut ladder (replaced by the hand-written P5 epilogue) deleted: 1159 lines less code between the P5 and P6 loops
# speedup vs baseline: 1.0037x; 1.0014x over previous
.LBB0_764:
	v_lshl_add_u32 v147, s30, 8, v150
	v_lshl_or_b32 v145, s28, 8, v152
	s_ashr_i32 s13, s30, 3
	s_mul_hi_i32 s23, s13, 0xc000
	s_mul_i32 s13, s13, 0xc000
	s_add_u32 s13, s64, s13
	s_addc_u32 s23, s65, s23
	s_add_u32 s30, s13, 0x4000
	s_addc_u32 s31, s23, 0
	s_add_u32 s28, s13, 0x8000
	s_addc_u32 s29, s23, 0
	v_readlane_b32 s52, v253, 24
	v_readlane_b32 s53, v253, 25
	v_readlane_b32 s66, v253, 38
	v_readlane_b32 s67, v253, 39
	v_lshlrev_b32_e32 v145, 2, v145
	v_lshl_add_u32 v146, v147, 13, v145
	v_lshlrev_b32_e32 v147, 2, v147
	v_xor_b32_e32 v196, 16, v156
	v_xor_b32_e32 v197, 32, v156
	v_lshlrev_b32_e32 v196, 2, v196
	v_lshlrev_b32_e32 v197, 2, v197
	global_load_dwordx4 v[158:161], v145, s[30:31] offset:0
	global_load_dwordx4 v[162:165], v145, s[30:31] offset:16
	global_load_dwordx4 v[166:169], v145, s[30:31] offset:512
	global_load_dwordx4 v[170:173], v145, s[30:31] offset:528
	v_mov_b32_e32 v144, v146
	global_load_dwordx4 v[220:223], v144, s[52:53] offset:0
	global_load_dwordx4 v[224:227], v144, s[52:53] offset:16
	global_load_dwordx4 v[228:231], v144, s[52:53] offset:512
	global_load_dwordx4 v[232:235], v144, s[52:53] offset:528
	v_add_u32_e32 v144, 0x20000, v146
	global_load_dwordx4 v[236:239], v144, s[52:53] offset:0
	global_load_dwordx4 v[240:243], v144, s[52:53] offset:16
	global_load_dwordx4 v[244:247], v144, s[52:53] offset:512
	global_load_dwordx4 v[248:251], v144, s[52:53] offset:528
	global_load_dwordx4 v[174:177], v145, s[28:29] offset:0
	global_load_dwordx4 v[178:181], v145, s[28:29] offset:16
	global_load_dwordx4 v[182:185], v145, s[28:29] offset:512
	global_load_dwordx4 v[186:189], v145, s[28:29] offset:528
	global_load_dwordx4 v[204:207], v145, s[66:67] offset:0
	global_load_dwordx4 v[208:211], v145, s[66:67] offset:16
	global_load_dwordx4 v[212:215], v145, s[66:67] offset:512
	global_load_dwordx4 v[216:219], v145, s[66:67] offset:528
	s_waitcnt vmcnt(0)
	v_pk_add_f32 v[174:175], v[174:175], 1.0 op_sel_hi:[1,0]
	v_pk_add_f32 v[176:177], v[176:177], 1.0 op_sel_hi:[1,0]
	v_pk_mul_f32 v[174:175], v[204:205], v[174:175]
	v_pk_mul_f32 v[176:177], v[206:207], v[176:177]
	v_pk_add_f32 v[178:179], v[178:179], 1.0 op_sel_hi:[1,0]
	v_pk_add_f32 v[180:181], v[180:181], 1.0 op_sel_hi:[1,0]
	v_pk_mul_f32 v[178:179], v[208:209], v[178:179]
	v_pk_mul_f32 v[180:181], v[210:211], v[180:181]
	v_pk_add_f32 v[182:183], v[182:183], 1.0 op_sel_hi:[1,0]
	v_pk_add_f32 v[184:185], v[184:185], 1.0 op_sel_hi:[1,0]
	v_pk_mul_f32 v[182:183], v[212:213], v[182:183]
	v_pk_mul_f32 v[184:185], v[214:215], v[184:185]
	v_pk_add_f32 v[186:187], v[186:187], 1.0 op_sel_hi:[1,0]
	v_pk_add_f32 v[188:189], v[188:189], 1.0 op_sel_hi:[1,0]
	v_pk_mul_f32 v[186:187], v[216:217], v[186:187]
	v_pk_mul_f32 v[188:189], v[218:219], v[188:189]
	s_waitcnt vmcnt(12)
	v_pk_fma_f32 v[124:125], v[124:125], v[158:159], v[220:221]
	v_pk_fma_f32 v[126:127], v[126:127], v[160:161], v[222:223]
	v_pk_fma_f32 v[120:121], v[120:121], v[162:163], v[224:225]
	v_pk_fma_f32 v[122:123], v[122:123], v[164:165], v[226:227]
	v_pk_fma_f32 v[116:117], v[116:117], v[166:167], v[228:229]
	v_pk_fma_f32 v[118:119], v[118:119], v[168:169], v[230:231]
	v_pk_fma_f32 v[112:113], v[112:113], v[170:171], v[232:233]
	v_pk_fma_f32 v[114:115], v[114:115], v[172:173], v[234:235]
	v_mov_b32_e32 v194, v146
	v_lshrrev_b32_e32 v198, 1, v194
	v_add_u32_e32 v144, 0x40000, v146
	global_load_dwordx4 v[220:223], v144, s[52:53] offset:0
	global_load_dwordx4 v[224:227], v144, s[52:53] offset:16
	global_load_dwordx4 v[228:231], v144, s[52:53] offset:512
	global_load_dwordx4 v[232:235], v144, s[52:53] offset:528
	global_store_dwordx4 v194, v[124:127], s[14:15] offset:0
	global_store_dwordx4 v194, v[120:123], s[14:15] offset:16
	global_store_dwordx4 v194, v[116:119], s[14:15] offset:512
	global_store_dwordx4 v194, v[112:115], s[14:15] offset:528
	v_pk_mul_f32 v[204:205], v[124:125], v[174:175]
	v_pk_mul_f32 v[206:207], v[126:127], v[176:177]
	v_cvt_pk_bf16_f32 v200, v204, v205
	v_cvt_pk_bf16_f32 v201, v206, v207
	v_pk_mul_f32 v[204:205], v[120:121], v[178:179]
	v_pk_mul_f32 v[206:207], v[122:123], v[180:181]
	v_cvt_pk_bf16_f32 v202, v204, v205
	v_cvt_pk_bf16_f32 v203, v206, v207
	global_store_dwordx4 v198, v[200:203], s[20:21]
	v_pk_mul_f32 v[204:205], v[116:117], v[182:183]
	v_pk_mul_f32 v[206:207], v[118:119], v[184:185]
	v_cvt_pk_bf16_f32 v208, v204, v205
	v_cvt_pk_bf16_f32 v209, v206, v207
	v_pk_mul_f32 v[204:205], v[112:113], v[186:187]
	v_pk_mul_f32 v[206:207], v[114:115], v[188:189]
	v_cvt_pk_bf16_f32 v210, v204, v205
	v_cvt_pk_bf16_f32 v211, v206, v207
	global_store_dwordx4 v198, v[208:211], s[20:21] offset:256
	v_mul_f32_e32 v190, v125, v125
	v_mul_f32_e32 v195, v127, v127
	v_fmac_f32_e32 v190, v124, v124
	v_fmac_f32_e32 v195, v126, v126
	v_add_f32_e32 v190, v190, v195
	v_mul_f32_e32 v191, v121, v121
	v_mul_f32_e32 v195, v123, v123
	v_fmac_f32_e32 v191, v120, v120
	v_fmac_f32_e32 v195, v122, v122
	v_add_f32_e32 v191, v191, v195
	v_mul_f32_e32 v192, v117, v117
	v_mul_f32_e32 v195, v119, v119
	v_fmac_f32_e32 v192, v116, v116
	v_fmac_f32_e32 v195, v118, v118
	v_add_f32_e32 v192, v192, v195
	v_mul_f32_e32 v193, v113, v113
	v_mul_f32_e32 v195, v115, v115
	v_fmac_f32_e32 v193, v112, v112
	v_fmac_f32_e32 v195, v114, v114
	v_add_f32_e32 v193, v193, v195
	v_add_f32_e32 v190, v190, v191
	v_add_f32_e32 v190, v190, v192
	v_add_f32_e32 v190, v190, v193
	ds_bpermute_b32 v195, v196, v190
	s_waitcnt lgkmcnt(0)
	v_add_f32_e32 v190, v190, v195
	ds_bpermute_b32 v195, v197, v190
	s_waitcnt lgkmcnt(0)
	v_add_f32_e32 v212, v190, v195
	s_waitcnt vmcnt(18)
	v_pk_fma_f32 v[108:109], v[108:109], v[158:159], v[236:237]
	v_pk_fma_f32 v[110:111], v[110:111], v[160:161], v[238:239]
	v_pk_fma_f32 v[104:105], v[104:105], v[162:163], v[240:241]
	v_pk_fma_f32 v[106:107], v[106:107], v[164:165], v[242:243]
	v_pk_fma_f32 v[100:101], v[100:101], v[166:167], v[244:245]
	v_pk_fma_f32 v[102:103], v[102:103], v[168:169], v[246:247]
	v_pk_fma_f32 v[96:97], v[96:97], v[170:171], v[248:249]
	v_pk_fma_f32 v[98:99], v[98:99], v[172:173], v[250:251]
	v_add_u32_e32 v194, 0x20000, v146
	v_lshrrev_b32_e32 v198, 1, v194
	v_add_u32_e32 v144, 0x60000, v146
	global_load_dwordx4 v[236:239], v144, s[52:53] offset:0
	global_load_dwordx4 v[240:243], v144, s[52:53] offset:16
	global_load_dwordx4 v[244:247], v144, s[52:53] offset:512
	global_load_dwordx4 v[248:251], v144, s[52:53] offset:528
	global_store_dwordx4 v194, v[108:111], s[14:15] offset:0
	global_store_dwordx4 v194, v[104:107], s[14:15] offset:16
	global_store_dwordx4 v194, v[100:103], s[14:15] offset:512
	global_store_dwordx4 v194, v[96:99], s[14:15] offset:528
	v_pk_mul_f32 v[204:205], v[108:109], v[174:175]
	v_pk_mul_f32 v[206:207], v[110:111], v[176:177]
	v_cvt_pk_bf16_f32 v200, v204, v205
	v_cvt_pk_bf16_f32 v201, v206, v207
	v_pk_mul_f32 v[204:205], v[104:105], v[178:179]
	v_pk_mul_f32 v[206:207], v[106:107], v[180:181]
	v_cvt_pk_bf16_f32 v202, v204, v205
	v_cvt_pk_bf16_f32 v203, v206, v207
	global_store_dwordx4 v198, v[200:203], s[20:21]
	v_pk_mul_f32 v[204:205], v[100:101], v[182:183]
	v_pk_mul_f32 v[206:207], v[102:103], v[184:185]
	v_cvt_pk_bf16_f32 v208, v204, v205
	v_cvt_pk_bf16_f32 v209, v206, v207
	v_pk_mul_f32 v[204:205], v[96:97], v[186:187]
	v_pk_mul_f32 v[206:207], v[98:99], v[188:189]
	v_cvt_pk_bf16_f32 v210, v204, v205
	v_cvt_pk_bf16_f32 v211, v206, v207
	global_store_dwordx4 v198, v[208:211], s[20:21] offset:256
	v_mul_f32_e32 v190, v109, v109
	v_mul_f32_e32 v195, v111, v111
	v_fmac_f32_e32 v190, v108, v108
	v_fmac_f32_e32 v195, v110, v110
	v_add_f32_e32 v190, v190, v195
	v_mul_f32_e32 v191, v105, v105
	v_mul_f32_e32 v195, v107, v107
	v_fmac_f32_e32 v191, v104, v104
	v_fmac_f32_e32 v195, v106, v106
	v_add_f32_e32 v191, v191, v195
	v_mul_f32_e32 v192, v101, v101
	v_mul_f32_e32 v195, v103, v103
	v_fmac_f32_e32 v192, v100, v100
	v_fmac_f32_e32 v195, v102, v102
	v_add_f32_e32 v192, v192, v195
	v_mul_f32_e32 v193, v97, v97
	v_mul_f32_e32 v195, v99, v99
	v_fmac_f32_e32 v193, v96, v96
	v_fmac_f32_e32 v195, v98, v98
	v_add_f32_e32 v193, v193, v195
	v_add_f32_e32 v190, v190, v191
	v_add_f32_e32 v190, v190, v192
	v_add_f32_e32 v190, v190, v193
	ds_bpermute_b32 v195, v196, v190
	s_waitcnt lgkmcnt(0)
	v_add_f32_e32 v190, v190, v195
	ds_bpermute_b32 v195, v197, v190
	s_waitcnt lgkmcnt(0)
	v_add_f32_e32 v213, v190, v195
	s_waitcnt vmcnt(16)
	v_pk_fma_f32 v[92:93], v[92:93], v[158:159], v[220:221]
	v_pk_fma_f32 v[94:95], v[94:95], v[160:161], v[222:223]
	v_pk_fma_f32 v[88:89], v[88:89], v[162:163], v[224:225]
	v_pk_fma_f32 v[90:91], v[90:91], v[164:165], v[226:227]
	v_pk_fma_f32 v[84:85], v[84:85], v[166:167], v[228:229]
	v_pk_fma_f32 v[86:87], v[86:87], v[168:169], v[230:231]
	v_pk_fma_f32 v[80:81], v[80:81], v[170:171], v[232:233]
	v_pk_fma_f32 v[82:83], v[82:83], v[172:173], v[234:235]
	v_add_u32_e32 v194, 0x40000, v146
	v_lshrrev_b32_e32 v198, 1, v194
	v_add_u32_e32 v144, 0x100000, v146
	global_load_dwordx4 v[220:223], v144, s[52:53] offset:0
	global_load_dwordx4 v[224:227], v144, s[52:53] offset:16
	global_load_dwordx4 v[228:231], v144, s[52:53] offset:512
	global_load_dwordx4 v[232:235], v144, s[52:53] offset:528
	global_store_dwordx4 v194, v[92:95], s[14:15] offset:0
	global_store_dwordx4 v194, v[88:91], s[14:15] offset:16
	global_store_dwordx4 v194, v[84:87], s[14:15] offset:512
	global_store_dwordx4 v194, v[80:83], s[14:15] offset:528
	v_pk_mul_f32 v[204:205], v[92:93], v[174:175]
	v_pk_mul_f32 v[206:207], v[94:95], v[176:177]
	v_cvt_pk_bf16_f32 v200, v204, v205
	v_cvt_pk_bf16_f32 v201, v206, v207
	v_pk_mul_f32 v[204:205], v[88:89], v[178:179]
	v_pk_mul_f32 v[206:207], v[90:91], v[180:181]
	v_cvt_pk_bf16_f32 v202, v204, v205
	v_cvt_pk_bf16_f32 v203, v206, v207
	global_store_dwordx4 v198, v[200:203], s[20:21]
	v_pk_mul_f32 v[204:205], v[84:85], v[182:183]
	v_pk_mul_f32 v[206:207], v[86:87], v[184:185]
	v_cvt_pk_bf16_f32 v208, v204, v205
	v_cvt_pk_bf16_f32 v209, v206, v207
	v_pk_mul_f32 v[204:205], v[80:81], v[186:187]
	v_pk_mul_f32 v[206:207], v[82:83], v[188:189]
	v_cvt_pk_bf16_f32 v210, v204, v205
	v_cvt_pk_bf16_f32 v211, v206, v207
	global_store_dwordx4 v198, v[208:211], s[20:21] offset:256
	v_mul_f32_e32 v190, v93, v93
	v_mul_f32_e32 v195, v95, v95
	v_fmac_f32_e32 v190, v92, v92
	v_fmac_f32_e32 v195, v94, v94
	v_add_f32_e32 v190, v190, v195
	v_mul_f32_e32 v191, v89, v89
	v_mul_f32_e32 v195, v91, v91
	v_fmac_f32_e32 v191, v88, v88
	v_fmac_f32_e32 v195, v90, v90
	v_add_f32_e32 v191, v191, v195
	v_mul_f32_e32 v192, v85, v85
	v_mul_f32_e32 v195, v87, v87
	v_fmac_f32_e32 v192, v84, v84
	v_fmac_f32_e32 v195, v86, v86
	v_add_f32_e32 v192, v192, v195
	v_mul_f32_e32 v193, v81, v81
	v_mul_f32_e32 v195, v83, v83
	v_fmac_f32_e32 v193, v80, v80
	v_fmac_f32_e32 v195, v82, v82
	v_add_f32_e32 v193, v193, v195
	v_add_f32_e32 v190, v190, v191
	v_add_f32_e32 v190, v190, v192
	v_add_f32_e32 v190, v190, v193
	ds_bpermute_b32 v195, v196, v190
	s_waitcnt lgkmcnt(0)
	v_add_f32_e32 v190, v190, v195
	ds_bpermute_b32 v195, v197, v190
	s_waitcnt lgkmcnt(0)
	v_add_f32_e32 v214, v190, v195
	s_waitcnt vmcnt(16)
	v_pk_fma_f32 v[76:77], v[76:77], v[158:159], v[236:237]
	v_pk_fma_f32 v[78:79], v[78:79], v[160:161], v[238:239]
	v_pk_fma_f32 v[72:73], v[72:73], v[162:163], v[240:241]
	v_pk_fma_f32 v[74:75], v[74:75], v[164:165], v[242:243]
	v_pk_fma_f32 v[68:69], v[68:69], v[166:167], v[244:245]
	v_pk_fma_f32 v[70:71], v[70:71], v[168:169], v[246:247]
	v_pk_fma_f32 v[64:65], v[64:65], v[170:171], v[248:249]
	v_pk_fma_f32 v[66:67], v[66:67], v[172:173], v[250:251]
	v_add_u32_e32 v194, 0x60000, v146
	v_lshrrev_b32_e32 v198, 1, v194
	v_add_u32_e32 v144, 0x120000, v146
	global_load_dwordx4 v[236:239], v144, s[52:53] offset:0
	global_load_dwordx4 v[240:243], v144, s[52:53] offset:16
	global_load_dwordx4 v[244:247], v144, s[52:53] offset:512
	global_load_dwordx4 v[248:251], v144, s[52:53] offset:528
	global_store_dwordx4 v194, v[76:79], s[14:15] offset:0
	global_store_dwordx4 v194, v[72:75], s[14:15] offset:16
	global_store_dwordx4 v194, v[68:71], s[14:15] offset:512
	global_store_dwordx4 v194, v[64:67], s[14:15] offset:528
	v_pk_mul_f32 v[204:205], v[76:77], v[174:175]
	v_pk_mul_f32 v[206:207], v[78:79], v[176:177]
	v_cvt_pk_bf16_f32 v200, v204, v205
	v_cvt_pk_bf16_f32 v201, v206, v207
	v_pk_mul_f32 v[204:205], v[72:73], v[178:179]
	v_pk_mul_f32 v[206:207], v[74:75], v[180:181]
	v_cvt_pk_bf16_f32 v202, v204, v205
	v_cvt_pk_bf16_f32 v203, v206, v207
	global_store_dwordx4 v198, v[200:203], s[20:21]
	v_pk_mul_f32 v[204:205], v[68:69], v[182:183]
	v_pk_mul_f32 v[206:207], v[70:71], v[184:185]
	v_cvt_pk_bf16_f32 v208, v204, v205
	v_cvt_pk_bf16_f32 v209, v206, v207
	v_pk_mul_f32 v[204:205], v[64:65], v[186:187]
	v_pk_mul_f32 v[206:207], v[66:67], v[188:189]
	v_cvt_pk_bf16_f32 v210, v204, v205
	v_cvt_pk_bf16_f32 v211, v206, v207
	global_store_dwordx4 v198, v[208:211], s[20:21] offset:256
	v_mul_f32_e32 v190, v77, v77
	v_mul_f32_e32 v195, v79, v79
	v_fmac_f32_e32 v190, v76, v76
	v_fmac_f32_e32 v195, v78, v78
	v_add_f32_e32 v190, v190, v195
	v_mul_f32_e32 v191, v73, v73
	v_mul_f32_e32 v195, v75, v75
	v_fmac_f32_e32 v191, v72, v72
	v_fmac_f32_e32 v195, v74, v74
	v_add_f32_e32 v191, v191, v195
	v_mul_f32_e32 v192, v69, v69
	v_mul_f32_e32 v195, v71, v71
	v_fmac_f32_e32 v192, v68, v68
	v_fmac_f32_e32 v195, v70, v70
	v_add_f32_e32 v192, v192, v195
	v_mul_f32_e32 v193, v65, v65
	v_mul_f32_e32 v195, v67, v67
	v_fmac_f32_e32 v193, v64, v64
	v_fmac_f32_e32 v195, v66, v66
	v_add_f32_e32 v193, v193, v195
	v_add_f32_e32 v190, v190, v191
	v_add_f32_e32 v190, v190, v192
	v_add_f32_e32 v190, v190, v193
	ds_bpermute_b32 v195, v196, v190
	s_waitcnt lgkmcnt(0)
	v_add_f32_e32 v190, v190, v195
	ds_bpermute_b32 v195, v197, v190
	s_waitcnt lgkmcnt(0)
	v_add_f32_e32 v215, v190, v195
	s_waitcnt vmcnt(16)
	v_pk_fma_f32 v[60:61], v[60:61], v[158:159], v[220:221]
	v_pk_fma_f32 v[62:63], v[62:63], v[160:161], v[222:223]
	v_pk_fma_f32 v[56:57], v[56:57], v[162:163], v[224:225]
	v_pk_fma_f32 v[58:59], v[58:59], v[164:165], v[226:227]
	v_pk_fma_f32 v[52:53], v[52:53], v[166:167], v[228:229]
	v_pk_fma_f32 v[54:55], v[54:55], v[168:169], v[230:231]
	v_pk_fma_f32 v[48:49], v[48:49], v[170:171], v[232:233]
	v_pk_fma_f32 v[50:51], v[50:51], v[172:173], v[234:235]
	v_add_u32_e32 v194, 0x100000, v146
	v_lshrrev_b32_e32 v198, 1, v194
	v_add_u32_e32 v144, 0x140000, v146
	global_load_dwordx4 v[220:223], v144, s[52:53] offset:0
	global_load_dwordx4 v[224:227], v144, s[52:53] offset:16
	global_load_dwordx4 v[228:231], v144, s[52:53] offset:512
	global_load_dwordx4 v[232:235], v144, s[52:53] offset:528
	global_store_dwordx4 v194, v[60:63], s[14:15] offset:0
	global_store_dwordx4 v194, v[56:59], s[14:15] offset:16
	global_store_dwordx4 v194, v[52:55], s[14:15] offset:512
	global_store_dwordx4 v194, v[48:51], s[14:15] offset:528
	v_pk_mul_f32 v[204:205], v[60:61], v[174:175]
	v_pk_mul_f32 v[206:207], v[62:63], v[176:177]
	v_cvt_pk_bf16_f32 v200, v204, v205
	v_cvt_pk_bf16_f32 v201, v206, v207
	v_pk_mul_f32 v[204:205], v[56:57], v[178:179]
	v_pk_mul_f32 v[206:207], v[58:59], v[180:181]
	v_cvt_pk_bf16_f32 v202, v204, v205
	v_cvt_pk_bf16_f32 v203, v206, v207
	global_store_dwordx4 v198, v[200:203], s[20:21]
	v_pk_mul_f32 v[204:205], v[52:53], v[182:183]
	v_pk_mul_f32 v[206:207], v[54:55], v[184:185]
	v_cvt_pk_bf16_f32 v208, v204, v205
	v_cvt_pk_bf16_f32 v209, v206, v207
	v_pk_mul_f32 v[204:205], v[48:49], v[186:187]
	v_pk_mul_f32 v[206:207], v[50:51], v[188:189]
	v_cvt_pk_bf16_f32 v210, v204, v205
	v_cvt_pk_bf16_f32 v211, v206, v207
	global_store_dwordx4 v198, v[208:211], s[20:21] offset:256
	v_mul_f32_e32 v190, v61, v61
	v_mul_f32_e32 v195, v63, v63
	v_fmac_f32_e32 v190, v60, v60
	v_fmac_f32_e32 v195, v62, v62
	v_add_f32_e32 v190, v190, v195
	v_mul_f32_e32 v191, v57, v57
	v_mul_f32_e32 v195, v59, v59
	v_fmac_f32_e32 v191, v56, v56
	v_fmac_f32_e32 v195, v58, v58
	v_add_f32_e32 v191, v191, v195
	v_mul_f32_e32 v192, v53, v53
	v_mul_f32_e32 v195, v55, v55
	v_fmac_f32_e32 v192, v52, v52
	v_fmac_f32_e32 v195, v54, v54
	v_add_f32_e32 v192, v192, v195
	v_mul_f32_e32 v193, v49, v49
	v_mul_f32_e32 v195, v51, v51
	v_fmac_f32_e32 v193, v48, v48
	v_fmac_f32_e32 v195, v50, v50
	v_add_f32_e32 v193, v193, v195
	v_add_f32_e32 v190, v190, v191
	v_add_f32_e32 v190, v190, v192
	v_add_f32_e32 v190, v190, v193
	ds_bpermute_b32 v195, v196, v190
	s_waitcnt lgkmcnt(0)
	v_add_f32_e32 v190, v190, v195
	ds_bpermute_b32 v195, v197, v190
	s_waitcnt lgkmcnt(0)
	v_add_f32_e32 v216, v190, v195
	s_waitcnt vmcnt(16)
	v_pk_fma_f32 v[44:45], v[44:45], v[158:159], v[236:237]
	v_pk_fma_f32 v[46:47], v[46:47], v[160:161], v[238:239]
	v_pk_fma_f32 v[40:41], v[40:41], v[162:163], v[240:241]
	v_pk_fma_f32 v[42:43], v[42:43], v[164:165], v[242:243]
	v_pk_fma_f32 v[36:37], v[36:37], v[166:167], v[244:245]
	v_pk_fma_f32 v[38:39], v[38:39], v[168:169], v[246:247]
	v_pk_fma_f32 v[32:33], v[32:33], v[170:171], v[248:249]
	v_pk_fma_f32 v[34:35], v[34:35], v[172:173], v[250:251]
	v_add_u32_e32 v194, 0x120000, v146
	v_lshrrev_b32_e32 v198, 1, v194
	v_add_u32_e32 v144, 0x160000, v146
	global_load_dwordx4 v[236:239], v144, s[52:53] offset:0
	global_load_dwordx4 v[240:243], v144, s[52:53] offset:16
	global_load_dwordx4 v[244:247], v144, s[52:53] offset:512
	global_load_dwordx4 v[248:251], v144, s[52:53] offset:528
	global_store_dwordx4 v194, v[44:47], s[14:15] offset:0
	global_store_dwordx4 v194, v[40:43], s[14:15] offset:16
	global_store_dwordx4 v194, v[36:39], s[14:15] offset:512
	global_store_dwordx4 v194, v[32:35], s[14:15] offset:528
	v_pk_mul_f32 v[204:205], v[44:45], v[174:175]
	v_pk_mul_f32 v[206:207], v[46:47], v[176:177]
	v_cvt_pk_bf16_f32 v200, v204, v205
	v_cvt_pk_bf16_f32 v201, v206, v207
	v_pk_mul_f32 v[204:205], v[40:41], v[178:179]
	v_pk_mul_f32 v[206:207], v[42:43], v[180:181]
	v_cvt_pk_bf16_f32 v202, v204, v205
	v_cvt_pk_bf16_f32 v203, v206, v207
	global_store_dwordx4 v198, v[200:203], s[20:21]
	v_pk_mul_f32 v[204:205], v[36:37], v[182:183]
	v_pk_mul_f32 v[206:207], v[38:39], v[184:185]
	v_cvt_pk_bf16_f32 v208, v204, v205
	v_cvt_pk_bf16_f32 v209, v206, v207
	v_pk_mul_f32 v[204:205], v[32:33], v[186:187]
	v_pk_mul_f32 v[206:207], v[34:35], v[188:189]
	v_cvt_pk_bf16_f32 v210, v204, v205
	v_cvt_pk_bf16_f32 v211, v206, v207
	global_store_dwordx4 v198, v[208:211], s[20:21] offset:256
	v_mul_f32_e32 v190, v45, v45
	v_mul_f32_e32 v195, v47, v47
	v_fmac_f32_e32 v190, v44, v44
	v_fmac_f32_e32 v195, v46, v46
	v_add_f32_e32 v190, v190, v195
	v_mul_f32_e32 v191, v41, v41
	v_mul_f32_e32 v195, v43, v43
	v_fmac_f32_e32 v191, v40, v40
	v_fmac_f32_e32 v195, v42, v42
	v_add_f32_e32 v191, v191, v195
	v_mul_f32_e32 v192, v37, v37
	v_mul_f32_e32 v195, v39, v39
	v_fmac_f32_e32 v192, v36, v36
	v_fmac_f32_e32 v195, v38, v38
	v_add_f32_e32 v192, v192, v195
	v_mul_f32_e32 v193, v33, v33
	v_mul_f32_e32 v195, v35, v35
	v_fmac_f32_e32 v193, v32, v32
	v_fmac_f32_e32 v195, v34, v34
	v_add_f32_e32 v193, v193, v195
	v_add_f32_e32 v190, v190, v191
	v_add_f32_e32 v190, v190, v192
	v_add_f32_e32 v190, v190, v193
	ds_bpermute_b32 v195, v196, v190
	s_waitcnt lgkmcnt(0)
	v_add_f32_e32 v190, v190, v195
	ds_bpermute_b32 v195, v197, v190
	s_waitcnt lgkmcnt(0)
	v_add_f32_e32 v217, v190, v195
	s_waitcnt vmcnt(16)
	v_pk_fma_f32 v[28:29], v[28:29], v[158:159], v[220:221]
	v_pk_fma_f32 v[30:31], v[30:31], v[160:161], v[222:223]
	v_pk_fma_f32 v[24:25], v[24:25], v[162:163], v[224:225]
	v_pk_fma_f32 v[26:27], v[26:27], v[164:165], v[226:227]
	v_pk_fma_f32 v[20:21], v[20:21], v[166:167], v[228:229]
	v_pk_fma_f32 v[22:23], v[22:23], v[168:169], v[230:231]
	v_pk_fma_f32 v[16:17], v[16:17], v[170:171], v[232:233]
	v_pk_fma_f32 v[18:19], v[18:19], v[172:173], v[234:235]
	v_add_u32_e32 v194, 0x140000, v146
	v_lshrrev_b32_e32 v198, 1, v194
	global_store_dwordx4 v194, v[28:31], s[14:15] offset:0
	global_store_dwordx4 v194, v[24:27], s[14:15] offset:16
	global_store_dwordx4 v194, v[20:23], s[14:15] offset:512
	global_store_dwordx4 v194, v[16:19], s[14:15] offset:528
	v_pk_mul_f32 v[204:205], v[28:29], v[174:175]
	v_pk_mul_f32 v[206:207], v[30:31], v[176:177]
	v_cvt_pk_bf16_f32 v200, v204, v205
	v_cvt_pk_bf16_f32 v201, v206, v207
	v_pk_mul_f32 v[204:205], v[24:25], v[178:179]
	v_pk_mul_f32 v[206:207], v[26:27], v[180:181]
	v_cvt_pk_bf16_f32 v202, v204, v205
	v_cvt_pk_bf16_f32 v203, v206, v207
	global_store_dwordx4 v198, v[200:203], s[20:21]
	v_pk_mul_f32 v[204:205], v[20:21], v[182:183]
	v_pk_mul_f32 v[206:207], v[22:23], v[184:185]
	v_cvt_pk_bf16_f32 v208, v204, v205
	v_cvt_pk_bf16_f32 v209, v206, v207
	v_pk_mul_f32 v[204:205], v[16:17], v[186:187]
	v_pk_mul_f32 v[206:207], v[18:19], v[188:189]
	v_cvt_pk_bf16_f32 v210, v204, v205
	v_cvt_pk_bf16_f32 v211, v206, v207
	global_store_dwordx4 v198, v[208:211], s[20:21] offset:256
	v_mul_f32_e32 v190, v29, v29
	v_mul_f32_e32 v195, v31, v31
	v_fmac_f32_e32 v190, v28, v28
	v_fmac_f32_e32 v195, v30, v30
	v_add_f32_e32 v190, v190, v195
	v_mul_f32_e32 v191, v25, v25
	v_mul_f32_e32 v195, v27, v27
	v_fmac_f32_e32 v191, v24, v24
	v_fmac_f32_e32 v195, v26, v26
	v_add_f32_e32 v191, v191, v195
	v_mul_f32_e32 v192, v21, v21
	v_mul_f32_e32 v195, v23, v23
	v_fmac_f32_e32 v192, v20, v20
	v_fmac_f32_e32 v195, v22, v22
	v_add_f32_e32 v192, v192, v195
	v_mul_f32_e32 v193, v17, v17
	v_mul_f32_e32 v195, v19, v19
	v_fmac_f32_e32 v193, v16, v16
	v_fmac_f32_e32 v195, v18, v18
	v_add_f32_e32 v193, v193, v195
	v_add_f32_e32 v190, v190, v191
	v_add_f32_e32 v190, v190, v192
	v_add_f32_e32 v190, v190, v193
	ds_bpermute_b32 v195, v196, v190
	s_waitcnt lgkmcnt(0)
	v_add_f32_e32 v190, v190, v195
	ds_bpermute_b32 v195, v197, v190
	s_waitcnt lgkmcnt(0)
	v_add_f32_e32 v218, v190, v195
	s_waitcnt vmcnt(12)
	v_pk_fma_f32 v[12:13], v[12:13], v[158:159], v[236:237]
	v_pk_fma_f32 v[14:15], v[14:15], v[160:161], v[238:239]
	v_pk_fma_f32 v[8:9], v[8:9], v[162:163], v[240:241]
	v_pk_fma_f32 v[10:11], v[10:11], v[164:165], v[242:243]
	v_pk_fma_f32 v[4:5], v[4:5], v[166:167], v[244:245]
	v_pk_fma_f32 v[6:7], v[6:7], v[168:169], v[246:247]
	v_pk_fma_f32 v[0:1], v[0:1], v[170:171], v[248:249]
	v_pk_fma_f32 v[2:3], v[2:3], v[172:173], v[250:251]
	v_add_u32_e32 v194, 0x160000, v146
	v_lshrrev_b32_e32 v198, 1, v194
	global_store_dwordx4 v194, v[12:15], s[14:15] offset:0
	global_store_dwordx4 v194, v[8:11], s[14:15] offset:16
	global_store_dwordx4 v194, v[4:7], s[14:15] offset:512
	global_store_dwordx4 v194, v[0:3], s[14:15] offset:528
	v_pk_mul_f32 v[204:205], v[12:13], v[174:175]
	v_pk_mul_f32 v[206:207], v[14:15], v[176:177]
	v_cvt_pk_bf16_f32 v200, v204, v205
	v_cvt_pk_bf16_f32 v201, v206, v207
	v_pk_mul_f32 v[204:205], v[8:9], v[178:179]
	v_pk_mul_f32 v[206:207], v[10:11], v[180:181]
	v_cvt_pk_bf16_f32 v202, v204, v205
	v_cvt_pk_bf16_f32 v203, v206, v207
	global_store_dwordx4 v198, v[200:203], s[20:21]
	v_pk_mul_f32 v[204:205], v[4:5], v[182:183]
	v_pk_mul_f32 v[206:207], v[6:7], v[184:185]
	v_cvt_pk_bf16_f32 v208, v204, v205
	v_cvt_pk_bf16_f32 v209, v206, v207
	v_pk_mul_f32 v[204:205], v[0:1], v[186:187]
	v_pk_mul_f32 v[206:207], v[2:3], v[188:189]
	v_cvt_pk_bf16_f32 v210, v204, v205
	v_cvt_pk_bf16_f32 v211, v206, v207
	global_store_dwordx4 v198, v[208:211], s[20:21] offset:256
	v_mul_f32_e32 v190, v13, v13
	v_mul_f32_e32 v195, v15, v15
	v_fmac_f32_e32 v190, v12, v12
	v_fmac_f32_e32 v195, v14, v14
	v_add_f32_e32 v190, v190, v195
	v_mul_f32_e32 v191, v9, v9
	v_mul_f32_e32 v195, v11, v11
	v_fmac_f32_e32 v191, v8, v8
	v_fmac_f32_e32 v195, v10, v10
	v_add_f32_e32 v191, v191, v195
	v_mul_f32_e32 v192, v5, v5
	v_mul_f32_e32 v195, v7, v7
	v_fmac_f32_e32 v192, v4, v4
	v_fmac_f32_e32 v195, v6, v6
	v_add_f32_e32 v192, v192, v195
	v_mul_f32_e32 v193, v1, v1
	v_mul_f32_e32 v195, v3, v3
	v_fmac_f32_e32 v193, v0, v0
	v_fmac_f32_e32 v195, v2, v2
	v_add_f32_e32 v193, v193, v195
	v_add_f32_e32 v190, v190, v191
	v_add_f32_e32 v190, v190, v192
	v_add_f32_e32 v190, v190, v193
	ds_bpermute_b32 v195, v196, v190
	s_waitcnt lgkmcnt(0)
	v_add_f32_e32 v190, v190, v195
	ds_bpermute_b32 v195, v197, v190
	s_waitcnt lgkmcnt(0)
	v_add_f32_e32 v219, v190, v195
	s_and_saveexec_b64 s[30:31], s[0:1]
	global_atomic_add_f32 v147, v212, s[18:19]
	global_atomic_add_f32 v147, v213, s[18:19] offset:64
	global_atomic_add_f32 v147, v214, s[18:19] offset:128
	global_atomic_add_f32 v147, v215, s[18:19] offset:192
	global_atomic_add_f32 v147, v216, s[18:19] offset:512
	global_atomic_add_f32 v147, v217, s[18:19] offset:576
	global_atomic_add_f32 v147, v218, s[18:19] offset:640
	global_atomic_add_f32 v147, v219, s[18:19] offset:704
	s_or_b64 exec, exec, s[30:31]
	s_branch .Lp5_epi_tail
.Lp5_epi_tail:
	s_andn2_b64 vcc, exec, s[40:41]
	s_mov_b64 s[28:29], -1
	s_cbranch_vccnz .LBB0_753
	s_andn2_b64 vcc, exec, s[4:5]
	s_cbranch_vccnz .LBB0_752
	s_barrier
	s_branch .LBB0_752
